# P9 row pass: the first bf16 piece joins the batched loads too (one wait per non-tail row), on top of v62
# speedup vs baseline: 1.0100x; 1.0022x over previous
.LBB0_998:
	s_nop 0
	v_add_co_u32_e32 v66, vcc, 0x1000, v132
	global_load_dwordx2 v[166:167], v[132:133], off nt
	global_load_dwordx2 v[164:165], v[132:133], off offset:512 nt
	global_load_dwordx2 v[162:163], v[132:133], off offset:1024 nt
	global_load_dwordx2 v[160:161], v[132:133], off offset:1536 nt
	global_load_dwordx2 v[158:159], v[132:133], off offset:2048 nt
	global_load_dwordx2 v[156:157], v[132:133], off offset:2560 nt
	global_load_dwordx2 v[154:155], v[132:133], off offset:3072 nt
	global_load_dwordx2 v[152:153], v[132:133], off offset:3584 nt
	v_addc_co_u32_e32 v67, vcc, 0, v133, vcc
	global_load_dwordx2 v[150:151], v[66:67], off nt
	global_load_dwordx2 v[148:149], v[66:67], off offset:512 nt
	global_load_dwordx2 v[146:147], v[66:67], off offset:1024 nt
	global_load_dwordx2 v[144:145], v[66:67], off offset:1536 nt
	global_load_dwordx2 v[142:143], v[66:67], off offset:2048 nt
	global_load_dwordx2 v[140:141], v[66:67], off offset:2560 nt
	global_load_dwordx2 v[138:139], v[66:67], off offset:3072 nt
	global_load_dwordx2 v[136:137], v[66:67], off offset:3584 nt
	s_cmpk_lt_i32 s4, 0x2000
	s_cselect_b64 s[0:1], -1, 0
	s_or_b64 s[16:17], s[14:15], s[0:1]
	s_add_i32 s0, s4, 0xffffe000
	s_lshr_b32 s2, s0, 8
	s_lshl_b64 s[0:1], s[2:3], 21
	s_add_u32 s0, s21, s0
	s_addc_u32 s1, s22, s1
	s_and_b32 s2, s23, 0xff00
	s_lshl_b32 s2, s2, 1
	s_add_u32 s0, s0, s2
	s_mov_b64 s[18:19], -1
	s_addc_u32 s1, s1, 0
	s_and_b64 vcc, exec, s[16:17]
	s_cbranch_vccz .LBB0_1000
	v_add_co_u32_e32 v66, vcc, 0xce000000, v132
	s_mov_b64 s[18:19], 0
	s_nop 0
	v_addc_co_u32_e32 v67, vcc, -1, v133, vcc
	global_load_dwordx2 v[68:69], v[66:67], off nt
.LBB0_1000:
	s_andn2_b64 vcc, exec, s[18:19]
	v_lshl_add_u64 v[168:169], s[0:1], 0, v[134:135]
	s_cbranch_vccnz .LBB0_1002
	v_add_co_u32_e32 v68, vcc, 0x800000, v168
	global_load_dwordx2 v[66:67], v[168:169], off
	s_nop 0
	v_addc_co_u32_e32 v69, vcc, 0, v169, vcc
	v_add_co_u32_e32 v70, vcc, 0x1000000, v168
	global_load_dwordx2 v[68:69], v[68:69], off
	s_nop 0
	v_addc_co_u32_e32 v71, vcc, 0, v169, vcc
	v_add_co_u32_e32 v72, vcc, 0x1800000, v168
	global_load_dwordx2 v[70:71], v[70:71], off
	s_nop 0
	v_addc_co_u32_e32 v73, vcc, 0, v169, vcc
	global_load_dwordx2 v[72:73], v[72:73], off
	s_waitcnt vmcnt(3)
	v_lshlrev_b32_e32 v74, 16, v66
	v_and_b32_e32 v75, 0xffff0000, v66
	v_lshlrev_b32_e32 v66, 16, v67
	v_and_b32_e32 v67, 0xffff0000, v67
	s_waitcnt vmcnt(2)
	v_lshlrev_b32_e32 v76, 16, v68
	v_and_b32_e32 v77, 0xffff0000, v68
	v_lshlrev_b32_e32 v68, 16, v69
	v_and_b32_e32 v69, 0xffff0000, v69
	v_pk_add_f32 v[66:67], v[66:67], v[68:69]
	s_waitcnt vmcnt(1)
	v_lshlrev_b32_e32 v78, 16, v70
	v_and_b32_e32 v79, 0xffff0000, v70
	v_lshlrev_b32_e32 v70, 16, v71
	v_and_b32_e32 v71, 0xffff0000, v71
	s_waitcnt vmcnt(0)
	v_lshlrev_b32_e32 v68, 16, v72
	v_and_b32_e32 v69, 0xffff0000, v72
	v_lshlrev_b32_e32 v72, 16, v73
	v_and_b32_e32 v73, 0xffff0000, v73
	v_pk_add_f32 v[74:75], v[74:75], v[76:77]
	v_pk_add_f32 v[76:77], v[78:79], v[68:69]
	v_pk_add_f32 v[68:69], v[70:71], v[72:73]
	s_nop 0
	v_pk_add_f32 v[68:69], v[66:67], v[68:69]
	v_pk_add_f32 v[66:67], v[74:75], v[76:77]
.LBB0_1002:
	v_cndmask_b32_e64 v70, 0, 1, s[16:17]
	v_cmp_ne_u32_e64 s[0:1], 1, v70
	s_andn2_b64 vcc, exec, s[16:17]
	s_mov_b64 s[16:17], -1
	s_cbranch_vccnz .LBB0_1032
	v_add_co_u32_e32 v70, vcc, 0xce001000, v132
	s_nop 1
	v_addc_co_u32_e32 v71, vcc, -1, v133, vcc
	global_load_dwordx2 v[72:73], v[70:71], off offset:-3584 nt
	v_add_co_u32_e32 v74, vcc, 0xce001000, v132
	s_nop 1
	v_addc_co_u32_e32 v75, vcc, -1, v133, vcc
	global_load_dwordx2 v[76:77], v[74:75], off offset:-3072 nt
	v_add_co_u32_e32 v78, vcc, 0xce001000, v132
	s_nop 1
	v_addc_co_u32_e32 v79, vcc, -1, v133, vcc
	global_load_dwordx2 v[80:81], v[78:79], off offset:-2560 nt
	v_add_co_u32_e32 v82, vcc, 0xce001000, v132
	s_nop 1
	v_addc_co_u32_e32 v83, vcc, -1, v133, vcc
	global_load_dwordx2 v[84:85], v[82:83], off offset:-2048 nt
	v_add_co_u32_e32 v86, vcc, 0xce001000, v132
	s_nop 1
	v_addc_co_u32_e32 v87, vcc, -1, v133, vcc
	global_load_dwordx2 v[88:89], v[86:87], off offset:-1536 nt
	v_add_co_u32_e32 v90, vcc, 0xce001000, v132
	s_nop 1
	v_addc_co_u32_e32 v91, vcc, -1, v133, vcc
	global_load_dwordx2 v[92:93], v[90:91], off offset:-1024 nt
	v_add_co_u32_e32 v94, vcc, 0xce001000, v132
	s_nop 1
	v_addc_co_u32_e32 v95, vcc, -1, v133, vcc
	global_load_dwordx2 v[96:97], v[94:95], off offset:-512 nt
	v_add_co_u32_e32 v98, vcc, 0xce001000, v132
	s_nop 1
	v_addc_co_u32_e32 v99, vcc, -1, v133, vcc
	global_load_dwordx2 v[100:101], v[98:99], off nt
	v_add_co_u32_e32 v102, vcc, 0xce002000, v132
	s_nop 1
	v_addc_co_u32_e32 v103, vcc, -1, v133, vcc
	global_load_dwordx2 v[104:105], v[102:103], off offset:-3584 nt
	v_add_co_u32_e32 v106, vcc, 0xce002000, v132
	s_nop 1
	v_addc_co_u32_e32 v107, vcc, -1, v133, vcc
	global_load_dwordx2 v[108:109], v[106:107], off offset:-3072 nt
	v_add_co_u32_e32 v110, vcc, 0xce002000, v132
	s_nop 1
	v_addc_co_u32_e32 v111, vcc, -1, v133, vcc
	global_load_dwordx2 v[112:113], v[110:111], off offset:-2560 nt
	v_add_co_u32_e32 v114, vcc, 0xce002000, v132
	s_nop 1
	v_addc_co_u32_e32 v115, vcc, -1, v133, vcc
	global_load_dwordx2 v[116:117], v[114:115], off offset:-2048 nt
	v_add_co_u32_e32 v118, vcc, 0xce002000, v132
	s_nop 1
	v_addc_co_u32_e32 v119, vcc, -1, v133, vcc
	global_load_dwordx2 v[120:121], v[118:119], off offset:-1536 nt
	v_add_co_u32_e32 v122, vcc, 0xce002000, v132
	s_nop 1
	v_addc_co_u32_e32 v123, vcc, -1, v133, vcc
	global_load_dwordx2 v[124:125], v[122:123], off offset:-1024 nt
	v_add_co_u32_e32 v126, vcc, 0xce002000, v132
	s_nop 1
	v_addc_co_u32_e32 v127, vcc, -1, v133, vcc
	global_load_dwordx2 v[128:129], v[126:127], off offset:-512 nt
	s_waitcnt vmcnt(0)
	v_lshlrev_b32_e32 v66, 16, v68
	v_and_b32_e32 v67, 0xffff0000, v68
	v_lshlrev_b32_e32 v68, 16, v69
	v_and_b32_e32 v69, 0xffff0000, v69
	v_lshlrev_b32_e32 v70, 16, v72
	v_and_b32_e32 v71, 0xffff0000, v72
	v_lshlrev_b32_e32 v72, 16, v73
	v_and_b32_e32 v73, 0xffff0000, v73
	v_lshlrev_b32_e32 v74, 16, v76
	v_and_b32_e32 v75, 0xffff0000, v76
	v_lshlrev_b32_e32 v76, 16, v77
	v_and_b32_e32 v77, 0xffff0000, v77
	v_lshlrev_b32_e32 v78, 16, v80
	v_and_b32_e32 v79, 0xffff0000, v80
	v_lshlrev_b32_e32 v80, 16, v81
	v_and_b32_e32 v81, 0xffff0000, v81
	v_lshlrev_b32_e32 v82, 16, v84
	v_and_b32_e32 v83, 0xffff0000, v84
	v_lshlrev_b32_e32 v84, 16, v85
	v_and_b32_e32 v85, 0xffff0000, v85
	v_lshlrev_b32_e32 v86, 16, v88
	v_and_b32_e32 v87, 0xffff0000, v88
	v_lshlrev_b32_e32 v88, 16, v89
	v_and_b32_e32 v89, 0xffff0000, v89
	v_lshlrev_b32_e32 v90, 16, v92
	v_and_b32_e32 v91, 0xffff0000, v92
	v_lshlrev_b32_e32 v92, 16, v93
	v_and_b32_e32 v93, 0xffff0000, v93
	v_lshlrev_b32_e32 v94, 16, v96
	v_and_b32_e32 v95, 0xffff0000, v96
	v_lshlrev_b32_e32 v96, 16, v97
	v_and_b32_e32 v97, 0xffff0000, v97
	v_lshlrev_b32_e32 v98, 16, v100
	v_and_b32_e32 v99, 0xffff0000, v100
	v_lshlrev_b32_e32 v100, 16, v101
	v_and_b32_e32 v101, 0xffff0000, v101
	v_lshlrev_b32_e32 v102, 16, v104
	v_and_b32_e32 v103, 0xffff0000, v104
	v_lshlrev_b32_e32 v104, 16, v105
	v_and_b32_e32 v105, 0xffff0000, v105
	v_lshlrev_b32_e32 v106, 16, v108
	v_and_b32_e32 v107, 0xffff0000, v108
	v_lshlrev_b32_e32 v108, 16, v109
	v_and_b32_e32 v109, 0xffff0000, v109
	v_lshlrev_b32_e32 v110, 16, v112
	v_and_b32_e32 v111, 0xffff0000, v112
	v_lshlrev_b32_e32 v112, 16, v113
	v_and_b32_e32 v113, 0xffff0000, v113
	v_lshlrev_b32_e32 v114, 16, v116
	v_and_b32_e32 v115, 0xffff0000, v116
	v_lshlrev_b32_e32 v116, 16, v117
	v_and_b32_e32 v117, 0xffff0000, v117
	v_lshlrev_b32_e32 v118, 16, v120
	v_and_b32_e32 v119, 0xffff0000, v120
	v_lshlrev_b32_e32 v120, 16, v121
	v_and_b32_e32 v121, 0xffff0000, v121
	v_lshlrev_b32_e32 v122, 16, v124
	v_and_b32_e32 v123, 0xffff0000, v124
	v_lshlrev_b32_e32 v124, 16, v125
	v_and_b32_e32 v125, 0xffff0000, v125
	v_lshlrev_b32_e32 v126, 16, v128
	v_and_b32_e32 v127, 0xffff0000, v128
	v_lshlrev_b32_e32 v128, 16, v129
	v_and_b32_e32 v129, 0xffff0000, v129
	s_branch .LBB0_997
	v_add_co_u32_e32 v70, vcc, 0xce001000, v132
	s_nop 1
	v_addc_co_u32_e32 v71, vcc, -1, v133, vcc
	global_load_dwordx2 v[72:73], v[70:71], off offset:-3584 nt
	s_waitcnt vmcnt(0)
	v_lshlrev_b32_e32 v70, 16, v72
	v_and_b32_e32 v71, 0xffff0000, v72
	v_lshlrev_b32_e32 v72, 16, v73
	v_and_b32_e32 v73, 0xffff0000, v73
	s_cbranch_execz .LBB0_1033
